# plus: FF1 output (HH) stored write-through (sc1) so the following grid barrier's L2 writeback has less to flush
# baseline (speedup 1.0000x reference)
.LBB0_859:
	v_lshl_add_u32 v152, s80, 8, v146
	v_lshl_or_b32 v144, s81, 8, v148
	v_ashrrev_i32_e32 v153, 31, v152
	v_max_f32_e32 v120, v120, v120
	v_ashrrev_i32_e32 v145, 31, v144
	v_lshlrev_b64 v[154:155], 13, v[152:153]
	v_max_f32_e32 v120, 0, v120
	v_max_f32_e32 v121, v121, v121
	v_max_f32_e32 v122, v122, v122
	v_max_f32_e32 v123, v123, v123
	v_lshl_add_u64 v[154:155], s[16:17], 0, v[154:155]
	v_lshlrev_b64 v[156:157], 1, v[144:145]
	v_max_f32_e32 v124, v124, v124
	v_mul_f32_e32 v120, v120, v120
	v_max_f32_e32 v121, 0, v121
	v_max_f32_e32 v125, v125, v125
	v_max_f32_e32 v122, 0, v122
	v_max_f32_e32 v126, v126, v126
	v_max_f32_e32 v123, 0, v123
	v_max_f32_e32 v127, v127, v127
	v_max_f32_e32 v112, v112, v112
	v_lshl_add_u64 v[144:145], v[154:155], 0, v[156:157]
	v_max_f32_e32 v124, 0, v124
	v_max_f32_e32 v125, 0, v125
	v_mul_f32_e32 v121, v121, v121
	v_max_f32_e32 v126, 0, v126
	v_mul_f32_e32 v122, v122, v122
	v_max_f32_e32 v127, 0, v127
	v_mul_f32_e32 v123, v123, v123
	v_cvt_pk_bf16_f32 v120, v120, v121
	v_max_f32_e32 v112, 0, v112
	v_max_f32_e32 v113, v113, v113
	v_max_f32_e32 v114, v114, v114
	v_mul_f32_e32 v124, v124, v124
	v_mul_f32_e32 v125, v125, v125
	v_mul_f32_e32 v126, v126, v126
	v_mul_f32_e32 v127, v127, v127
	v_cvt_pk_bf16_f32 v121, v122, v123
	v_cvt_pk_bf16_f32 v122, v124, v125
	v_cvt_pk_bf16_f32 v123, v126, v127
	global_store_dwordx4 v[144:145], v[120:123], off sc1
	v_max_f32_e32 v113, 0, v113
	v_max_f32_e32 v114, 0, v114
	v_mul_f32_e32 v120, v112, v112
	v_max_f32_e32 v112, v117, v117
	v_max_f32_e32 v116, v116, v116
	v_max_f32_e32 v112, 0, v112
	v_mul_f32_e32 v117, v113, v113
	v_max_f32_e32 v113, v118, v118
	v_mul_f32_e32 v118, v114, v114
	v_max_f32_e32 v114, v119, v119
	v_max_f32_e32 v115, v115, v115
	v_max_f32_e32 v116, 0, v116
	v_mul_f32_e32 v112, v112, v112
	v_max_f32_e32 v113, 0, v113
	v_max_f32_e32 v114, 0, v114
	v_max_f32_e32 v115, 0, v115
	v_mul_f32_e32 v116, v116, v116
	v_mul_f32_e32 v113, v113, v113
	v_mul_f32_e32 v114, v114, v114
	v_mul_f32_e32 v115, v115, v115
	v_cvt_pk_bf16_f32 v112, v116, v112
	v_max_f32_e32 v104, v104, v104
	v_cvt_pk_bf16_f32 v113, v113, v114
	v_cvt_pk_bf16_f32 v114, v120, v117
	v_cvt_pk_bf16_f32 v115, v118, v115
	global_store_dwordx4 v[144:145], v[112:115], off offset:256 sc1
	v_max_f32_e32 v104, 0, v104
	v_max_f32_e32 v105, v105, v105
	v_or_b32_e32 v112, 16, v152
	v_max_f32_e32 v106, v106, v106
	v_ashrrev_i32_e32 v113, 31, v112
	v_mul_f32_e32 v114, v104, v104
	v_max_f32_e32 v104, v109, v109
	v_max_f32_e32 v105, 0, v105
	v_max_f32_e32 v106, 0, v106
	v_lshlrev_b64 v[112:113], 13, v[112:113]
	v_max_f32_e32 v108, v108, v108
	v_max_f32_e32 v104, 0, v104
	v_mul_f32_e32 v109, v105, v105
	v_max_f32_e32 v105, v110, v110
	v_mul_f32_e32 v110, v106, v106
	v_max_f32_e32 v106, v111, v111
	v_max_f32_e32 v107, v107, v107
	v_lshl_add_u64 v[112:113], s[16:17], 0, v[112:113]
	v_max_f32_e32 v108, 0, v108
	v_mul_f32_e32 v104, v104, v104
	v_max_f32_e32 v105, 0, v105
	v_max_f32_e32 v106, 0, v106
	v_max_f32_e32 v107, 0, v107
	v_max_f32_e32 v96, v96, v96
	v_lshl_add_u64 v[112:113], v[112:113], 0, v[156:157]
	v_mul_f32_e32 v108, v108, v108
	v_mul_f32_e32 v105, v105, v105
	v_mul_f32_e32 v106, v106, v106
	v_mul_f32_e32 v107, v107, v107
	v_cvt_pk_bf16_f32 v104, v108, v104
	v_max_f32_e32 v96, 0, v96
	v_max_f32_e32 v97, v97, v97
	v_max_f32_e32 v98, v98, v98
	v_cvt_pk_bf16_f32 v105, v105, v106
	v_cvt_pk_bf16_f32 v106, v114, v109
	v_cvt_pk_bf16_f32 v107, v110, v107
	global_store_dwordx4 v[112:113], v[104:107], off sc1
	v_max_f32_e32 v97, 0, v97
	v_max_f32_e32 v98, 0, v98
	v_mul_f32_e32 v104, v96, v96
	v_max_f32_e32 v96, v101, v101
	v_max_f32_e32 v100, v100, v100
	v_max_f32_e32 v96, 0, v96
	v_mul_f32_e32 v101, v97, v97
	v_max_f32_e32 v97, v102, v102
	v_mul_f32_e32 v102, v98, v98
	v_max_f32_e32 v98, v103, v103
	v_max_f32_e32 v99, v99, v99
	v_max_f32_e32 v100, 0, v100
	v_mul_f32_e32 v96, v96, v96
	v_max_f32_e32 v97, 0, v97
	v_max_f32_e32 v98, 0, v98
	v_max_f32_e32 v99, 0, v99
	v_mul_f32_e32 v100, v100, v100
	v_mul_f32_e32 v97, v97, v97
	v_mul_f32_e32 v98, v98, v98
	v_mul_f32_e32 v99, v99, v99
	v_cvt_pk_bf16_f32 v96, v100, v96
	v_max_f32_e32 v88, v88, v88
	v_cvt_pk_bf16_f32 v97, v97, v98
	v_cvt_pk_bf16_f32 v98, v104, v101
	v_cvt_pk_bf16_f32 v99, v102, v99
	global_store_dwordx4 v[112:113], v[96:99], off offset:256 sc1
	v_max_f32_e32 v88, 0, v88
	v_max_f32_e32 v89, v89, v89
	v_or_b32_e32 v96, 32, v152
	v_max_f32_e32 v90, v90, v90
	v_ashrrev_i32_e32 v97, 31, v96
	v_mul_f32_e32 v98, v88, v88
	v_max_f32_e32 v88, v93, v93
	v_max_f32_e32 v89, 0, v89
	v_max_f32_e32 v90, 0, v90
	v_lshlrev_b64 v[96:97], 13, v[96:97]
	v_max_f32_e32 v92, v92, v92
	v_max_f32_e32 v88, 0, v88
	v_mul_f32_e32 v93, v89, v89
	v_max_f32_e32 v89, v94, v94
	v_mul_f32_e32 v94, v90, v90
	v_max_f32_e32 v90, v95, v95
	v_max_f32_e32 v91, v91, v91
	v_lshl_add_u64 v[96:97], s[16:17], 0, v[96:97]
	v_max_f32_e32 v92, 0, v92
	v_mul_f32_e32 v88, v88, v88
	v_max_f32_e32 v89, 0, v89
	v_max_f32_e32 v90, 0, v90
	v_max_f32_e32 v91, 0, v91
	v_max_f32_e32 v80, v80, v80
	v_lshl_add_u64 v[96:97], v[96:97], 0, v[156:157]
	v_mul_f32_e32 v92, v92, v92
	v_mul_f32_e32 v89, v89, v89
	v_mul_f32_e32 v90, v90, v90
	v_mul_f32_e32 v91, v91, v91
	v_cvt_pk_bf16_f32 v88, v92, v88
	v_max_f32_e32 v80, 0, v80
	v_max_f32_e32 v81, v81, v81
	v_max_f32_e32 v82, v82, v82
	v_cvt_pk_bf16_f32 v89, v89, v90
	v_cvt_pk_bf16_f32 v90, v98, v93
	v_cvt_pk_bf16_f32 v91, v94, v91
	global_store_dwordx4 v[96:97], v[88:91], off sc1
	v_max_f32_e32 v81, 0, v81
	v_max_f32_e32 v82, 0, v82
	v_mul_f32_e32 v88, v80, v80
	v_max_f32_e32 v80, v85, v85
	v_max_f32_e32 v84, v84, v84
	v_max_f32_e32 v80, 0, v80
	v_mul_f32_e32 v85, v81, v81
	v_max_f32_e32 v81, v86, v86
	v_mul_f32_e32 v86, v82, v82
	v_max_f32_e32 v82, v87, v87
	v_max_f32_e32 v83, v83, v83
	v_max_f32_e32 v84, 0, v84
	v_mul_f32_e32 v80, v80, v80
	v_max_f32_e32 v81, 0, v81
	v_max_f32_e32 v82, 0, v82
	v_max_f32_e32 v83, 0, v83
	v_mul_f32_e32 v84, v84, v84
	v_mul_f32_e32 v81, v81, v81
	v_mul_f32_e32 v82, v82, v82
	v_mul_f32_e32 v83, v83, v83
	v_cvt_pk_bf16_f32 v80, v84, v80
	v_max_f32_e32 v72, v72, v72
	v_cvt_pk_bf16_f32 v81, v81, v82
	v_cvt_pk_bf16_f32 v82, v88, v85
	v_cvt_pk_bf16_f32 v83, v86, v83
	global_store_dwordx4 v[96:97], v[80:83], off offset:256 sc1
	v_max_f32_e32 v72, 0, v72
	v_max_f32_e32 v73, v73, v73
	v_or_b32_e32 v80, 48, v152
	v_max_f32_e32 v74, v74, v74
	v_ashrrev_i32_e32 v81, 31, v80
	v_mul_f32_e32 v82, v72, v72
	v_max_f32_e32 v72, v77, v77
	v_max_f32_e32 v73, 0, v73
	v_max_f32_e32 v74, 0, v74
	v_lshlrev_b64 v[80:81], 13, v[80:81]
	v_max_f32_e32 v76, v76, v76
	v_max_f32_e32 v72, 0, v72
	v_mul_f32_e32 v77, v73, v73
	v_max_f32_e32 v73, v78, v78
	v_mul_f32_e32 v78, v74, v74
	v_max_f32_e32 v74, v79, v79
	v_max_f32_e32 v75, v75, v75
	v_lshl_add_u64 v[80:81], s[16:17], 0, v[80:81]
	v_max_f32_e32 v76, 0, v76
	v_mul_f32_e32 v72, v72, v72
	v_max_f32_e32 v73, 0, v73
	v_max_f32_e32 v74, 0, v74
	v_max_f32_e32 v75, 0, v75
	v_max_f32_e32 v64, v64, v64
	v_max_f32_e32 v65, v65, v65
	v_max_f32_e32 v66, v66, v66
	v_lshl_add_u64 v[80:81], v[80:81], 0, v[156:157]
	v_mul_f32_e32 v76, v76, v76
	v_mul_f32_e32 v73, v73, v73
	v_mul_f32_e32 v74, v74, v74
	v_mul_f32_e32 v75, v75, v75
	v_cvt_pk_bf16_f32 v72, v76, v72
	v_max_f32_e32 v64, 0, v64
	v_max_f32_e32 v65, 0, v65
	v_max_f32_e32 v66, 0, v66
	v_cvt_pk_bf16_f32 v73, v73, v74
	v_cvt_pk_bf16_f32 v74, v82, v77
	v_cvt_pk_bf16_f32 v75, v78, v75
	global_store_dwordx4 v[80:81], v[72:75], off sc1
	v_max_f32_e32 v68, v68, v68
	v_max_f32_e32 v67, v67, v67
	v_mul_f32_e32 v72, v64, v64
	v_max_f32_e32 v64, v69, v69
	v_mul_f32_e32 v69, v65, v65
	v_max_f32_e32 v65, v70, v70
	v_mul_f32_e32 v70, v66, v66
	v_max_f32_e32 v66, v71, v71
	v_max_f32_e32 v64, 0, v64
	v_max_f32_e32 v65, 0, v65
	v_max_f32_e32 v66, 0, v66
	v_max_f32_e32 v68, 0, v68
	v_mul_f32_e32 v64, v64, v64
	v_mul_f32_e32 v65, v65, v65
	v_max_f32_e32 v67, 0, v67
	v_mul_f32_e32 v66, v66, v66
	v_max_f32_e32 v56, v56, v56
	v_mul_f32_e32 v68, v68, v68
	v_mul_f32_e32 v67, v67, v67
	v_cvt_pk_bf16_f32 v64, v68, v64
	v_cvt_pk_bf16_f32 v65, v65, v66
	v_cvt_pk_bf16_f32 v66, v72, v69
	v_max_f32_e32 v56, 0, v56
	v_max_f32_e32 v57, v57, v57
	v_max_f32_e32 v58, v58, v58
	v_cvt_pk_bf16_f32 v67, v70, v67
	global_store_dwordx4 v[80:81], v[64:67], off offset:256 sc1
	v_max_f32_e32 v60, v60, v60
	v_max_f32_e32 v57, 0, v57
	v_mul_f32_e32 v66, v56, v56
	v_max_f32_e32 v56, v61, v61
	v_max_f32_e32 v58, 0, v58
	v_max_f32_e32 v60, 0, v60
	v_max_f32_e32 v56, 0, v56
	v_mul_f32_e32 v61, v57, v57
	v_max_f32_e32 v57, v62, v62
	v_mul_f32_e32 v62, v58, v58
	v_max_f32_e32 v58, v63, v63
	v_mul_f32_e32 v60, v60, v60
	v_mul_f32_e32 v56, v56, v56
	v_max_f32_e32 v57, 0, v57
	v_max_f32_e32 v58, 0, v58
	v_max_f32_e32 v59, v59, v59
	v_mul_f32_e32 v57, v57, v57
	v_max_f32_e32 v59, 0, v59
	v_mul_f32_e32 v58, v58, v58
	v_cvt_pk_bf16_f32 v56, v60, v56
	v_add_co_u32_e32 v60, vcc, s69, v144
	v_max_f32_e32 v48, v48, v48
	v_max_f32_e32 v49, v49, v49
	v_max_f32_e32 v50, v50, v50
	v_mul_f32_e32 v59, v59, v59
	v_cvt_pk_bf16_f32 v57, v57, v58
	v_cvt_pk_bf16_f32 v58, v66, v61
	v_addc_co_u32_e32 v61, vcc, 0, v145, vcc
	v_max_f32_e32 v48, 0, v48
	v_max_f32_e32 v49, 0, v49
	v_max_f32_e32 v50, 0, v50
	v_cvt_pk_bf16_f32 v59, v62, v59
	global_store_dwordx4 v[60:61], v[56:59], off sc1
	v_max_f32_e32 v52, v52, v52
	v_max_f32_e32 v51, v51, v51
	v_mul_f32_e32 v56, v48, v48
	v_max_f32_e32 v48, v53, v53
	v_mul_f32_e32 v53, v49, v49
	v_max_f32_e32 v49, v54, v54
	v_mul_f32_e32 v54, v50, v50
	v_max_f32_e32 v50, v55, v55
	v_max_f32_e32 v48, 0, v48
	v_max_f32_e32 v49, 0, v49
	v_max_f32_e32 v50, 0, v50
	v_max_f32_e32 v52, 0, v52
	v_mul_f32_e32 v48, v48, v48
	v_mul_f32_e32 v49, v49, v49
	v_max_f32_e32 v51, 0, v51
	v_mul_f32_e32 v50, v50, v50
	v_max_f32_e32 v40, v40, v40
	v_lshl_add_u64 v[64:65], v[144:145], 0, s[50:51]
	v_mul_f32_e32 v52, v52, v52
	v_mul_f32_e32 v51, v51, v51
	v_cvt_pk_bf16_f32 v48, v52, v48
	v_cvt_pk_bf16_f32 v49, v49, v50
	v_cvt_pk_bf16_f32 v50, v56, v53
	v_max_f32_e32 v40, 0, v40
	v_max_f32_e32 v41, v41, v41
	v_max_f32_e32 v42, v42, v42
	v_cvt_pk_bf16_f32 v51, v54, v51
	global_store_dwordx4 v[64:65], v[48:51], off offset:256 sc1
	v_max_f32_e32 v44, v44, v44
	v_max_f32_e32 v41, 0, v41
	v_mul_f32_e32 v50, v40, v40
	v_max_f32_e32 v40, v45, v45
	v_max_f32_e32 v42, 0, v42
	v_max_f32_e32 v44, 0, v44
	v_max_f32_e32 v40, 0, v40
	v_mul_f32_e32 v45, v41, v41
	v_max_f32_e32 v41, v46, v46
	v_mul_f32_e32 v46, v42, v42
	v_max_f32_e32 v42, v47, v47
	v_mul_f32_e32 v44, v44, v44
	v_mul_f32_e32 v40, v40, v40
	v_max_f32_e32 v41, 0, v41
	v_max_f32_e32 v42, 0, v42
	v_max_f32_e32 v43, v43, v43
	v_mul_f32_e32 v41, v41, v41
	v_max_f32_e32 v43, 0, v43
	v_mul_f32_e32 v42, v42, v42
	v_cvt_pk_bf16_f32 v40, v44, v40
	v_add_co_u32_e32 v44, vcc, s71, v144
	v_max_f32_e32 v32, v32, v32
	v_max_f32_e32 v33, v33, v33
	v_max_f32_e32 v34, v34, v34
	v_mul_f32_e32 v43, v43, v43
	v_cvt_pk_bf16_f32 v41, v41, v42
	v_cvt_pk_bf16_f32 v42, v50, v45
	v_addc_co_u32_e32 v45, vcc, 0, v145, vcc
	v_max_f32_e32 v32, 0, v32
	v_max_f32_e32 v33, 0, v33
	v_max_f32_e32 v34, 0, v34
	v_cvt_pk_bf16_f32 v43, v46, v43
	global_store_dwordx4 v[44:45], v[40:43], off sc1
	v_max_f32_e32 v36, v36, v36
	v_max_f32_e32 v35, v35, v35
	v_mul_f32_e32 v40, v32, v32
	v_max_f32_e32 v32, v37, v37
	v_mul_f32_e32 v37, v33, v33
	v_max_f32_e32 v33, v38, v38
	v_mul_f32_e32 v38, v34, v34
	v_max_f32_e32 v34, v39, v39
	v_max_f32_e32 v32, 0, v32
	v_max_f32_e32 v33, 0, v33
	v_max_f32_e32 v34, 0, v34
	v_max_f32_e32 v36, 0, v36
	v_mul_f32_e32 v32, v32, v32
	v_mul_f32_e32 v33, v33, v33
	v_max_f32_e32 v35, 0, v35
	v_mul_f32_e32 v34, v34, v34
	v_max_f32_e32 v24, v24, v24
	v_lshl_add_u64 v[48:49], v[144:145], 0, s[52:53]
	v_mul_f32_e32 v36, v36, v36
	v_mul_f32_e32 v35, v35, v35
	v_cvt_pk_bf16_f32 v32, v36, v32
	v_cvt_pk_bf16_f32 v33, v33, v34
	v_cvt_pk_bf16_f32 v34, v40, v37
	v_max_f32_e32 v24, 0, v24
	v_max_f32_e32 v25, v25, v25
	v_max_f32_e32 v26, v26, v26
	v_cvt_pk_bf16_f32 v35, v38, v35
	global_store_dwordx4 v[48:49], v[32:35], off offset:256 sc1
	v_max_f32_e32 v28, v28, v28
	v_max_f32_e32 v25, 0, v25
	v_mul_f32_e32 v34, v24, v24
	v_max_f32_e32 v24, v29, v29
	v_max_f32_e32 v26, 0, v26
	v_max_f32_e32 v28, 0, v28
	v_max_f32_e32 v24, 0, v24
	v_mul_f32_e32 v29, v25, v25
	v_max_f32_e32 v25, v30, v30
	v_mul_f32_e32 v30, v26, v26
	v_max_f32_e32 v26, v31, v31
	v_mul_f32_e32 v28, v28, v28
	v_mul_f32_e32 v24, v24, v24
	v_max_f32_e32 v25, 0, v25
	v_max_f32_e32 v26, 0, v26
	v_max_f32_e32 v27, v27, v27
	v_mul_f32_e32 v25, v25, v25
	v_max_f32_e32 v27, 0, v27
	v_mul_f32_e32 v26, v26, v26
	v_cvt_pk_bf16_f32 v24, v28, v24
	v_add_co_u32_e32 v28, vcc, s72, v144
	v_max_f32_e32 v16, v16, v16
	v_max_f32_e32 v17, v17, v17
	v_max_f32_e32 v18, v18, v18
	v_mul_f32_e32 v27, v27, v27
	v_cvt_pk_bf16_f32 v25, v25, v26
	v_cvt_pk_bf16_f32 v26, v34, v29
	v_addc_co_u32_e32 v29, vcc, 0, v145, vcc
	v_max_f32_e32 v16, 0, v16
	v_max_f32_e32 v17, 0, v17
	v_max_f32_e32 v18, 0, v18
	v_cvt_pk_bf16_f32 v27, v30, v27
	global_store_dwordx4 v[28:29], v[24:27], off sc1
	v_max_f32_e32 v20, v20, v20
	v_max_f32_e32 v19, v19, v19
	v_mul_f32_e32 v24, v16, v16
	v_max_f32_e32 v16, v21, v21
	v_mul_f32_e32 v21, v17, v17
	v_max_f32_e32 v17, v22, v22
	v_mul_f32_e32 v22, v18, v18
	v_max_f32_e32 v18, v23, v23
	v_max_f32_e32 v16, 0, v16
	v_max_f32_e32 v17, 0, v17
	v_max_f32_e32 v18, 0, v18
	v_max_f32_e32 v20, 0, v20
	v_mul_f32_e32 v16, v16, v16
	v_mul_f32_e32 v17, v17, v17
	v_max_f32_e32 v19, 0, v19
	v_mul_f32_e32 v18, v18, v18
	v_max_f32_e32 v8, v8, v8
	v_lshl_add_u64 v[32:33], v[144:145], 0, s[54:55]
	v_mul_f32_e32 v20, v20, v20
	v_mul_f32_e32 v19, v19, v19
	v_cvt_pk_bf16_f32 v16, v20, v16
	v_cvt_pk_bf16_f32 v17, v17, v18
	v_cvt_pk_bf16_f32 v18, v24, v21
	v_max_f32_e32 v8, 0, v8
	v_max_f32_e32 v9, v9, v9
	v_max_f32_e32 v10, v10, v10
	v_cvt_pk_bf16_f32 v19, v22, v19
	global_store_dwordx4 v[32:33], v[16:19], off offset:256 sc1
	v_max_f32_e32 v12, v12, v12
	v_max_f32_e32 v9, 0, v9
	v_mul_f32_e32 v18, v8, v8
	v_max_f32_e32 v8, v13, v13
	v_max_f32_e32 v10, 0, v10
	v_max_f32_e32 v12, 0, v12
	v_max_f32_e32 v8, 0, v8
	v_mul_f32_e32 v13, v9, v9
	v_max_f32_e32 v9, v14, v14
	v_mul_f32_e32 v14, v10, v10
	v_max_f32_e32 v10, v15, v15
	v_mul_f32_e32 v12, v12, v12
	v_mul_f32_e32 v8, v8, v8
	v_max_f32_e32 v9, 0, v9
	v_max_f32_e32 v10, 0, v10
	v_max_f32_e32 v11, v11, v11
	v_mul_f32_e32 v9, v9, v9
	v_max_f32_e32 v11, 0, v11
	v_mul_f32_e32 v10, v10, v10
	v_cvt_pk_bf16_f32 v8, v12, v8
	v_add_co_u32_e32 v12, vcc, s75, v144
	v_max_f32_e32 v0, v0, v0
	v_max_f32_e32 v1, v1, v1
	v_max_f32_e32 v2, v2, v2
	v_mul_f32_e32 v11, v11, v11
	v_cvt_pk_bf16_f32 v9, v9, v10
	v_cvt_pk_bf16_f32 v10, v18, v13
	v_addc_co_u32_e32 v13, vcc, 0, v145, vcc
	v_max_f32_e32 v0, 0, v0
	v_max_f32_e32 v1, 0, v1
	v_max_f32_e32 v2, 0, v2
	v_cvt_pk_bf16_f32 v11, v14, v11
	global_store_dwordx4 v[12:13], v[8:11], off sc1
	v_max_f32_e32 v3, v3, v3
	v_max_f32_e32 v4, v4, v4
	v_mul_f32_e32 v8, v0, v0
	v_max_f32_e32 v0, v5, v5
	v_mul_f32_e32 v5, v1, v1
	v_max_f32_e32 v1, v6, v6
	v_mul_f32_e32 v6, v2, v2
	v_max_f32_e32 v2, v7, v7
	v_max_f32_e32 v0, 0, v0
	v_max_f32_e32 v1, 0, v1
	v_max_f32_e32 v2, 0, v2
	v_max_f32_e32 v3, 0, v3
	v_lshl_add_u64 v[16:17], v[144:145], 0, s[56:57]
	v_max_f32_e32 v4, 0, v4
	v_mul_f32_e32 v0, v0, v0
	v_mul_f32_e32 v1, v1, v1
	v_mul_f32_e32 v2, v2, v2
	v_mul_f32_e32 v3, v3, v3
	s_and_b64 vcc, exec, s[8:9]
	s_mov_b64 s[8:9], -1
	v_mul_f32_e32 v4, v4, v4
	v_cvt_pk_bf16_f32 v0, v4, v0
	v_cvt_pk_bf16_f32 v1, v1, v2
	v_cvt_pk_bf16_f32 v2, v8, v5
	v_cvt_pk_bf16_f32 v3, v6, v3
	global_store_dwordx4 v[16:17], v[0:3], off offset:256 sc1
	s_cbranch_vccnz .LBB0_843
	s_andn2_b64 vcc, exec, s[42:43]
	s_cbranch_vccnz .LBB0_842
	s_barrier
	s_branch .LBB0_842
